# FFN-in epilogue: activation (ACT) stores marked nt (streamed once to the next GEMM)
# baseline (speedup 1.0000x reference)
; DI float silu_f(float x) { return x * __builtin_amdgcn_rcpf(1.f + __expf(-x)); }
; #define EPI_LOOP_ROWS _Pragma("unroll") for (int ai = 0; ai < 2; ++ai) _Pragma("unroll") for (int m = 0; m < 4; ++m)
; DI u32x4 pack8(const f32x4 a, const f32x4 b) { return (u32x4){pack2(a[0], a[1]), pack2(a[2], a[3]), pack2(b[0], b[1]), pack2(b[2], b[3])}; }
;     DI void operator()(const AccT& acc, int brow, int bcol, int wr, int wc, int fr, int fq) const {
;         const int col = (bcol >> 1) + wc * 32 + fq * 8;
;         EPI_LOOP_ROWS { const size_t row = brow + ai * 128 + wr * 64 + m * 16 + fr; f32x4 o[2];
; #pragma unroll
;             for (int n = 0; n < 2; ++n) { const f32x4 g = acc[ai][0][m][n], u = acc[ai][1][m][n];
; #pragma unroll
;                 for (int j = 0; j < 4; ++j) o[n][j] = silu_f(g[j]) * u[j]; }
;             *(u32x4*)(ACT + row * DFF + col) = pack8(o[0], o[1]); }
;     }
.LBB0_766:
	v_mov_b32_e32 v144, v252
	s_ashr_i32 s9, s34, 1
	v_lshrrev_b32_e32 v146, 1, v144
	v_and_b32_e32 v147, 0x60, v146
	v_and_b32_e32 v146, 24, v146
	v_add3_u32 v146, v147, s9, v146
	v_mul_f32_e32 v147, 0xbfb8aa3b, v124
	v_exp_f32_e32 v147, v147
	v_mul_f32_e32 v148, 0xbfb8aa3b, v125
	v_exp_f32_e32 v149, v148
	v_and_b32_e32 v145, 15, v144
	v_add_f32_e32 v147, 1.0, v147
	v_rcp_f32_e32 v148, v147
	v_add_f32_e32 v147, 1.0, v149
	v_rcp_f32_e32 v149, v147
	v_ashrrev_i32_e32 v144, 2, v144
	v_and_b32_e32 v144, 0xffffffc0, v144
	v_add3_u32 v144, v145, s30, v144
	v_pk_mul_f32 v[124:125], v[124:125], v[148:149]
	v_mul_f32_e32 v145, 0xbfb8aa3b, v126
	v_mul_f32_e32 v148, 0xbfb8aa3b, v127
	v_exp_f32_e32 v145, v145
	v_exp_f32_e32 v148, v148
	v_pk_mul_f32 v[116:117], v[124:125], v[116:117]
	v_ashrrev_i32_e32 v147, 31, v146
	v_add_f32_e32 v124, 1.0, v145
	v_add_f32_e32 v125, 1.0, v148
	v_mul_f32_e32 v145, 0xbfb8aa3b, v120
	v_rcp_f32_e32 v124, v124
	v_rcp_f32_e32 v125, v125
	v_exp_f32_e32 v145, v145
	v_mul_f32_e32 v148, 0xbfb8aa3b, v121
	v_exp_f32_e32 v148, v148
	v_pk_mul_f32 v[124:125], v[126:127], v[124:125]
	v_add_f32_e32 v126, 1.0, v145
	v_mul_f32_e32 v145, 0xbfb8aa3b, v122
	v_add_f32_e32 v127, 1.0, v148
	v_exp_f32_e32 v145, v145
	v_mul_f32_e32 v148, 0xbfb8aa3b, v123
	v_exp_f32_e32 v149, v148
	v_rcp_f32_e32 v126, v126
	v_add_f32_e32 v145, 1.0, v145
	v_rcp_f32_e32 v127, v127
	v_rcp_f32_e32 v148, v145
	v_add_f32_e32 v145, 1.0, v149
	v_rcp_f32_e32 v149, v145
	v_pk_mul_f32 v[120:121], v[120:121], v[126:127]
	v_pk_mul_f32 v[118:119], v[124:125], v[118:119]
	v_pk_mul_f32 v[112:113], v[120:121], v[112:113]
	v_pk_mul_f32 v[120:121], v[122:123], v[148:149]
	v_cvt_pk_bf16_f32 v116, v116, v117
	v_pk_mul_f32 v[114:115], v[120:121], v[114:115]
	v_cvt_pk_bf16_f32 v117, v118, v119
	v_cvt_pk_bf16_f32 v119, v114, v115
	v_mul_f32_e32 v114, 0xbfb8aa3b, v108
	v_exp_f32_e32 v122, v114
	v_mul_f32_e32 v114, 0xbfb8aa3b, v109
	v_exp_f32_e32 v123, v114
	v_cvt_pk_bf16_f32 v118, v112, v113
	v_mov_b64_e32 v[112:113], s[96:97]
	v_mad_i64_i32 v[120:121], s[14:15], v144, s47, v[112:113]
	v_lshlrev_b64 v[114:115], 1, v[146:147]
	v_add_f32_e32 v122, 1.0, v122
	v_add_f32_e32 v123, 1.0, v123
	v_lshl_add_u64 v[120:121], v[120:121], 0, v[114:115]
	v_rcp_f32_e32 v122, v122
	v_rcp_f32_e32 v123, v123
	global_store_dwordx4 v[120:121], v[116:119], off nt
	s_andn2_b64 vcc, exec, s[6:7]
	s_mov_b64 s[6:7], -1
	v_mul_f32_e32 v116, 0xbfb8aa3b, v110
	v_mul_f32_e32 v117, 0xbfb8aa3b, v111
	v_exp_f32_e32 v116, v116
	v_exp_f32_e32 v117, v117
	v_pk_mul_f32 v[108:109], v[108:109], v[122:123]
	v_add_u32_e32 v118, 16, v144
	v_pk_mul_f32 v[100:101], v[108:109], v[100:101]
	v_add_f32_e32 v108, 1.0, v116
	v_add_f32_e32 v109, 1.0, v117
	v_mul_f32_e32 v116, 0xbfb8aa3b, v104
	v_mul_f32_e32 v117, 0xbfb8aa3b, v105
	v_rcp_f32_e32 v108, v108
	v_rcp_f32_e32 v109, v109
	v_exp_f32_e32 v116, v116
	v_exp_f32_e32 v117, v117
	v_pk_mul_f32 v[108:109], v[110:111], v[108:109]
	v_add_f32_e32 v110, 1.0, v116
	v_add_f32_e32 v111, 1.0, v117
	v_mul_f32_e32 v116, 0xbfb8aa3b, v106
	v_mul_f32_e32 v117, 0xbfb8aa3b, v107
	v_exp_f32_e32 v116, v116
	v_exp_f32_e32 v117, v117
	v_rcp_f32_e32 v110, v110
	v_rcp_f32_e32 v111, v111
	v_add_f32_e32 v116, 1.0, v116
	v_add_f32_e32 v117, 1.0, v117
	v_rcp_f32_e32 v116, v116
	v_rcp_f32_e32 v117, v117
	v_pk_mul_f32 v[104:105], v[104:105], v[110:111]
	v_pk_mul_f32 v[102:103], v[108:109], v[102:103]
	v_pk_mul_f32 v[104:105], v[104:105], v[96:97]
	v_pk_mul_f32 v[96:97], v[106:107], v[116:117]
	s_nop 0
	v_pk_mul_f32 v[106:107], v[96:97], v[98:99]
	v_cvt_pk_bf16_f32 v96, v100, v101
	v_mul_f32_e32 v100, 0xbfb8aa3b, v92
	v_cvt_pk_bf16_f32 v97, v102, v103
	v_exp_f32_e32 v102, v100
	v_mul_f32_e32 v100, 0xbfb8aa3b, v93
	v_exp_f32_e32 v103, v100
	v_mad_i64_i32 v[100:101], s[14:15], v118, s47, v[112:113]
	v_cvt_pk_bf16_f32 v98, v104, v105
	v_cvt_pk_bf16_f32 v99, v106, v107
	v_add_f32_e32 v102, 1.0, v102
	v_add_f32_e32 v103, 1.0, v103
	v_lshl_add_u64 v[100:101], v[100:101], 0, v[114:115]
	v_rcp_f32_e32 v102, v102
	v_rcp_f32_e32 v103, v103
	global_store_dwordx4 v[100:101], v[96:99], off nt
	v_pk_mul_f32 v[92:93], v[92:93], v[102:103]
	s_nop 0
	v_mul_f32_e32 v96, 0xbfb8aa3b, v94
	v_mul_f32_e32 v97, 0xbfb8aa3b, v95
	v_exp_f32_e32 v96, v96
	v_exp_f32_e32 v97, v97
	v_pk_mul_f32 v[84:85], v[92:93], v[84:85]
	v_add_u32_e32 v98, 32, v144
	v_add_f32_e32 v92, 1.0, v96
	v_add_f32_e32 v93, 1.0, v97
	v_mul_f32_e32 v96, 0xbfb8aa3b, v88
	v_mul_f32_e32 v97, 0xbfb8aa3b, v89
	v_rcp_f32_e32 v92, v92
	v_rcp_f32_e32 v93, v93
	v_exp_f32_e32 v96, v96
	v_exp_f32_e32 v97, v97
	v_pk_mul_f32 v[92:93], v[94:95], v[92:93]
	v_add_f32_e32 v94, 1.0, v96
	v_add_f32_e32 v95, 1.0, v97
	v_mul_f32_e32 v96, 0xbfb8aa3b, v90
	v_mul_f32_e32 v97, 0xbfb8aa3b, v91
	v_exp_f32_e32 v96, v96
	v_exp_f32_e32 v97, v97
	v_rcp_f32_e32 v94, v94
	v_rcp_f32_e32 v95, v95
	v_add_f32_e32 v96, 1.0, v96
	v_add_f32_e32 v97, 1.0, v97
	v_rcp_f32_e32 v96, v96
	v_rcp_f32_e32 v97, v97
	v_pk_mul_f32 v[88:89], v[88:89], v[94:95]
	v_pk_mul_f32 v[86:87], v[92:93], v[86:87]
	v_pk_mul_f32 v[88:89], v[88:89], v[80:81]
	v_pk_mul_f32 v[80:81], v[90:91], v[96:97]
	s_nop 0
	v_pk_mul_f32 v[90:91], v[80:81], v[82:83]
	v_cvt_pk_bf16_f32 v80, v84, v85
	v_mul_f32_e32 v84, 0xbfb8aa3b, v76
	v_cvt_pk_bf16_f32 v81, v86, v87
	v_exp_f32_e32 v86, v84
	v_mul_f32_e32 v84, 0xbfb8aa3b, v77
	v_exp_f32_e32 v87, v84
	v_mad_i64_i32 v[84:85], s[14:15], v98, s47, v[112:113]
	v_cvt_pk_bf16_f32 v82, v88, v89
	v_cvt_pk_bf16_f32 v83, v90, v91
	v_add_f32_e32 v86, 1.0, v86
	v_add_f32_e32 v87, 1.0, v87
	v_lshl_add_u64 v[84:85], v[84:85], 0, v[114:115]
	v_rcp_f32_e32 v86, v86
	v_rcp_f32_e32 v87, v87
; DI float silu_f(float x) { return x * __builtin_amdgcn_rcpf(1.f + __expf(-x)); }
; #define EPI_LOOP_ROWS _Pragma("unroll") for (int ai = 0; ai < 2; ++ai) _Pragma("unroll") for (int m = 0; m < 4; ++m)
; DI u32x4 pack8(const f32x4 a, const f32x4 b) { return (u32x4){pack2(a[0], a[1]), pack2(a[2], a[3]), pack2(b[0], b[1]), pack2(b[2], b[3])}; }
;     DI void operator()(const AccT& acc, int brow, int bcol, int wr, int wc, int fr, int fq) const {
;         const int col = (bcol >> 1) + wc * 32 + fq * 8;
;         EPI_LOOP_ROWS { const size_t row = brow + ai * 128 + wr * 64 + m * 16 + fr; f32x4 o[2];
; #pragma unroll
;             for (int n = 0; n < 2; ++n) { const f32x4 g = acc[ai][0][m][n], u = acc[ai][1][m][n];
; #pragma unroll
;                 for (int j = 0; j < 4; ++j) o[n][j] = silu_f(g[j]) * u[j]; }
;             *(u32x4*)(ACT + row * DFF + col) = pack8(o[0], o[1]); }
;     }
	global_store_dwordx4 v[84:85], v[80:83], off nt
	v_pk_mul_f32 v[76:77], v[76:77], v[86:87]
	s_nop 0
	v_mul_f32_e32 v80, 0xbfb8aa3b, v78
	v_mul_f32_e32 v81, 0xbfb8aa3b, v79
	v_exp_f32_e32 v80, v80
	v_exp_f32_e32 v81, v81
	v_pk_mul_f32 v[68:69], v[76:77], v[68:69]
	v_add_u32_e32 v82, 48, v144
	v_add_f32_e32 v76, 1.0, v80
	v_add_f32_e32 v77, 1.0, v81
	v_mul_f32_e32 v80, 0xbfb8aa3b, v72
	v_mul_f32_e32 v81, 0xbfb8aa3b, v73
	v_rcp_f32_e32 v76, v76
	v_rcp_f32_e32 v77, v77
	v_exp_f32_e32 v80, v80
	v_exp_f32_e32 v81, v81
	v_pk_mul_f32 v[76:77], v[78:79], v[76:77]
	v_add_f32_e32 v78, 1.0, v80
	v_add_f32_e32 v79, 1.0, v81
	v_mul_f32_e32 v80, 0xbfb8aa3b, v74
	v_mul_f32_e32 v81, 0xbfb8aa3b, v75
	v_exp_f32_e32 v80, v80
	v_exp_f32_e32 v81, v81
	v_rcp_f32_e32 v78, v78
	v_rcp_f32_e32 v79, v79
	v_add_f32_e32 v80, 1.0, v80
	v_add_f32_e32 v81, 1.0, v81
	v_rcp_f32_e32 v80, v80
	v_rcp_f32_e32 v81, v81
	v_pk_mul_f32 v[72:73], v[72:73], v[78:79]
	v_pk_mul_f32 v[70:71], v[76:77], v[70:71]
	v_pk_mul_f32 v[72:73], v[72:73], v[64:65]
	v_pk_mul_f32 v[64:65], v[74:75], v[80:81]
	s_nop 0
	v_pk_mul_f32 v[74:75], v[64:65], v[66:67]
	v_cvt_pk_bf16_f32 v64, v68, v69
	v_mul_f32_e32 v68, 0xbfb8aa3b, v60
	v_cvt_pk_bf16_f32 v65, v70, v71
	v_exp_f32_e32 v70, v68
	v_mul_f32_e32 v68, 0xbfb8aa3b, v61
	v_exp_f32_e32 v71, v68
	v_mad_i64_i32 v[68:69], s[14:15], v82, s47, v[112:113]
	v_cvt_pk_bf16_f32 v66, v72, v73
	v_cvt_pk_bf16_f32 v67, v74, v75
	v_add_f32_e32 v70, 1.0, v70
	v_add_f32_e32 v71, 1.0, v71
	v_lshl_add_u64 v[68:69], v[68:69], 0, v[114:115]
	v_rcp_f32_e32 v70, v70
	v_rcp_f32_e32 v71, v71
	global_store_dwordx4 v[68:69], v[64:67], off nt
	v_pk_mul_f32 v[60:61], v[60:61], v[70:71]
	s_nop 0
	v_mul_f32_e32 v64, 0xbfb8aa3b, v62
	v_mul_f32_e32 v65, 0xbfb8aa3b, v63
	v_exp_f32_e32 v64, v64
	v_exp_f32_e32 v65, v65
	v_pk_mul_f32 v[52:53], v[60:61], v[52:53]
	v_add_u32_e32 v66, 0x80, v144
	v_add_f32_e32 v60, 1.0, v64
	v_add_f32_e32 v61, 1.0, v65
	v_mul_f32_e32 v64, 0xbfb8aa3b, v56
	v_mul_f32_e32 v65, 0xbfb8aa3b, v57
	v_rcp_f32_e32 v60, v60
	v_rcp_f32_e32 v61, v61
	v_exp_f32_e32 v64, v64
	v_exp_f32_e32 v65, v65
	v_pk_mul_f32 v[60:61], v[62:63], v[60:61]
	v_add_f32_e32 v62, 1.0, v64
	v_add_f32_e32 v63, 1.0, v65
	v_mul_f32_e32 v64, 0xbfb8aa3b, v58
	v_mul_f32_e32 v65, 0xbfb8aa3b, v59
	v_exp_f32_e32 v64, v64
	v_exp_f32_e32 v65, v65
	v_rcp_f32_e32 v62, v62
	v_rcp_f32_e32 v63, v63
	v_add_f32_e32 v64, 1.0, v64
	v_add_f32_e32 v65, 1.0, v65
	v_rcp_f32_e32 v64, v64
	v_rcp_f32_e32 v65, v65
	v_pk_mul_f32 v[56:57], v[56:57], v[62:63]
	v_pk_mul_f32 v[54:55], v[60:61], v[54:55]
	v_pk_mul_f32 v[56:57], v[56:57], v[48:49]
	v_pk_mul_f32 v[48:49], v[58:59], v[64:65]
	s_nop 0
	v_pk_mul_f32 v[58:59], v[48:49], v[50:51]
	v_cvt_pk_bf16_f32 v48, v52, v53
	v_mul_f32_e32 v52, 0xbfb8aa3b, v44
	v_cvt_pk_bf16_f32 v49, v54, v55
	v_exp_f32_e32 v54, v52
	v_mul_f32_e32 v52, 0xbfb8aa3b, v45
	v_exp_f32_e32 v55, v52
	v_mad_i64_i32 v[52:53], s[14:15], v66, s47, v[112:113]
	v_cvt_pk_bf16_f32 v50, v56, v57
	v_cvt_pk_bf16_f32 v51, v58, v59
	v_add_f32_e32 v54, 1.0, v54
	v_add_f32_e32 v55, 1.0, v55
	v_lshl_add_u64 v[52:53], v[52:53], 0, v[114:115]
	v_rcp_f32_e32 v54, v54
	v_rcp_f32_e32 v55, v55
	global_store_dwordx4 v[52:53], v[48:51], off nt
	v_pk_mul_f32 v[44:45], v[44:45], v[54:55]
	s_nop 0
	v_mul_f32_e32 v48, 0xbfb8aa3b, v46
	v_mul_f32_e32 v49, 0xbfb8aa3b, v47
	v_exp_f32_e32 v48, v48
	v_exp_f32_e32 v49, v49
	v_pk_mul_f32 v[36:37], v[44:45], v[36:37]
	v_add_u32_e32 v50, 0x90, v144
	v_add_f32_e32 v44, 1.0, v48
	v_add_f32_e32 v45, 1.0, v49
	v_mul_f32_e32 v48, 0xbfb8aa3b, v40
	v_mul_f32_e32 v49, 0xbfb8aa3b, v41
	v_rcp_f32_e32 v44, v44
	v_rcp_f32_e32 v45, v45
	v_exp_f32_e32 v48, v48
	v_exp_f32_e32 v49, v49
	v_pk_mul_f32 v[44:45], v[46:47], v[44:45]
	v_add_f32_e32 v46, 1.0, v48
	v_add_f32_e32 v47, 1.0, v49
	v_mul_f32_e32 v48, 0xbfb8aa3b, v42
	v_mul_f32_e32 v49, 0xbfb8aa3b, v43
	v_exp_f32_e32 v48, v48
	v_exp_f32_e32 v49, v49
; DI float silu_f(float x) { return x * __builtin_amdgcn_rcpf(1.f + __expf(-x)); }
; #define BAR __builtin_amdgcn_s_barrier()
; #define EPI_LOOP_ROWS _Pragma("unroll") for (int ai = 0; ai < 2; ++ai) _Pragma("unroll") for (int m = 0; m < 4; ++m)
; DI u32x4 pack8(const f32x4 a, const f32x4 b) { return (u32x4){pack2(a[0], a[1]), pack2(a[2], a[3]), pack2(b[0], b[1]), pack2(b[2], b[3])}; }
; template <class Get, class Epi>
; DI void gemm_loop(int ntiles, int ld, char* shm, const Get& get, const Epi& epi) {
;     ...
;         if (wr == 0) BAR;
;         { int tx2 = threadIdx.x, brow2 = cur.brow, bcol2 = cur.bcol, Lo = L; asm volatile("" : "+v"(tx2), "+s"(brow2), "+s"(bcol2), "+s"(Lo));
;           const int wid2 = tx2 >> 6, lane2 = tx2 & 63; epi(Lo, acc, brow2, bcol2, wid2 >> 2, wid2 & 3, lane2 & 15, lane2 >> 4); }
;         if (!has_next) break;
;         G_ZERO;
;         cur = nxt; cA = nA; cB = nB; L = Ln;
;         if (wr == 1) BAR;
;     DI void operator()(const AccT& acc, int brow, int bcol, int wr, int wc, int fr, int fq) const {
;         const int col = (bcol >> 1) + wc * 32 + fq * 8;
;         EPI_LOOP_ROWS { const size_t row = brow + ai * 128 + wr * 64 + m * 16 + fr; f32x4 o[2];
; #pragma unroll
;             for (int n = 0; n < 2; ++n) { const f32x4 g = acc[ai][0][m][n], u = acc[ai][1][m][n];
; #pragma unroll
;                 for (int j = 0; j < 4; ++j) o[n][j] = silu_f(g[j]) * u[j]; }
;             *(u32x4*)(ACT + row * DFF + col) = pack8(o[0], o[1]); }
;     }
	v_rcp_f32_e32 v46, v46
	v_rcp_f32_e32 v47, v47
	v_add_f32_e32 v48, 1.0, v48
	v_add_f32_e32 v49, 1.0, v49
	v_rcp_f32_e32 v48, v48
	v_rcp_f32_e32 v49, v49
	v_pk_mul_f32 v[40:41], v[40:41], v[46:47]
	v_pk_mul_f32 v[38:39], v[44:45], v[38:39]
	v_pk_mul_f32 v[40:41], v[40:41], v[32:33]
	v_pk_mul_f32 v[32:33], v[42:43], v[48:49]
	s_nop 0
	v_pk_mul_f32 v[42:43], v[32:33], v[34:35]
	v_cvt_pk_bf16_f32 v32, v36, v37
	v_mul_f32_e32 v36, 0xbfb8aa3b, v28
	v_cvt_pk_bf16_f32 v33, v38, v39
	v_exp_f32_e32 v38, v36
	v_mul_f32_e32 v36, 0xbfb8aa3b, v29
	v_exp_f32_e32 v39, v36
	v_mad_i64_i32 v[36:37], s[14:15], v50, s47, v[112:113]
	v_cvt_pk_bf16_f32 v34, v40, v41
	v_cvt_pk_bf16_f32 v35, v42, v43
	v_add_f32_e32 v38, 1.0, v38
	v_add_f32_e32 v39, 1.0, v39
	v_lshl_add_u64 v[36:37], v[36:37], 0, v[114:115]
	v_rcp_f32_e32 v38, v38
	v_rcp_f32_e32 v39, v39
	global_store_dwordx4 v[36:37], v[32:35], off nt
	v_pk_mul_f32 v[28:29], v[28:29], v[38:39]
	s_nop 0
	v_mul_f32_e32 v32, 0xbfb8aa3b, v30
	v_mul_f32_e32 v33, 0xbfb8aa3b, v31
	v_exp_f32_e32 v32, v32
	v_exp_f32_e32 v33, v33
	v_pk_mul_f32 v[20:21], v[28:29], v[20:21]
	v_add_u32_e32 v34, 0xa0, v144
	v_add_f32_e32 v28, 1.0, v32
	v_add_f32_e32 v29, 1.0, v33
	v_mul_f32_e32 v32, 0xbfb8aa3b, v24
	v_mul_f32_e32 v33, 0xbfb8aa3b, v25
	v_rcp_f32_e32 v28, v28
	v_rcp_f32_e32 v29, v29
	v_exp_f32_e32 v32, v32
	v_exp_f32_e32 v33, v33
	v_pk_mul_f32 v[28:29], v[30:31], v[28:29]
	v_add_f32_e32 v30, 1.0, v32
	v_add_f32_e32 v31, 1.0, v33
	v_mul_f32_e32 v32, 0xbfb8aa3b, v26
	v_mul_f32_e32 v33, 0xbfb8aa3b, v27
	v_exp_f32_e32 v32, v32
	v_exp_f32_e32 v33, v33
	v_rcp_f32_e32 v30, v30
	v_rcp_f32_e32 v31, v31
	v_add_f32_e32 v32, 1.0, v32
	v_add_f32_e32 v33, 1.0, v33
	v_rcp_f32_e32 v32, v32
	v_rcp_f32_e32 v33, v33
	v_pk_mul_f32 v[24:25], v[24:25], v[30:31]
	v_pk_mul_f32 v[22:23], v[28:29], v[22:23]
	v_pk_mul_f32 v[24:25], v[24:25], v[16:17]
	v_pk_mul_f32 v[16:17], v[26:27], v[32:33]
	s_nop 0
	v_pk_mul_f32 v[26:27], v[16:17], v[18:19]
	v_cvt_pk_bf16_f32 v16, v20, v21
	v_mul_f32_e32 v20, 0xbfb8aa3b, v12
	v_cvt_pk_bf16_f32 v17, v22, v23
	v_exp_f32_e32 v22, v20
	v_mul_f32_e32 v20, 0xbfb8aa3b, v13
	v_exp_f32_e32 v23, v20
	v_mad_i64_i32 v[20:21], s[14:15], v34, s47, v[112:113]
	v_cvt_pk_bf16_f32 v18, v24, v25
	v_cvt_pk_bf16_f32 v19, v26, v27
	v_add_f32_e32 v22, 1.0, v22
	v_add_f32_e32 v23, 1.0, v23
	v_lshl_add_u64 v[20:21], v[20:21], 0, v[114:115]
	v_rcp_f32_e32 v22, v22
	v_rcp_f32_e32 v23, v23
	global_store_dwordx4 v[20:21], v[16:19], off nt
	v_pk_mul_f32 v[12:13], v[12:13], v[22:23]
	s_nop 0
	v_mul_f32_e32 v16, 0xbfb8aa3b, v14
	v_mul_f32_e32 v17, 0xbfb8aa3b, v15
	v_exp_f32_e32 v16, v16
	v_exp_f32_e32 v17, v17
	v_pk_mul_f32 v[4:5], v[12:13], v[4:5]
	v_add_u32_e32 v18, 0xb0, v144
	v_add_f32_e32 v12, 1.0, v16
	v_add_f32_e32 v13, 1.0, v17
	v_mul_f32_e32 v16, 0xbfb8aa3b, v8
	v_mul_f32_e32 v17, 0xbfb8aa3b, v9
	v_rcp_f32_e32 v12, v12
	v_rcp_f32_e32 v13, v13
	v_exp_f32_e32 v16, v16
	v_exp_f32_e32 v17, v17
	v_pk_mul_f32 v[12:13], v[14:15], v[12:13]
	v_add_f32_e32 v14, 1.0, v16
	v_add_f32_e32 v15, 1.0, v17
	v_mul_f32_e32 v16, 0xbfb8aa3b, v10
	v_mul_f32_e32 v17, 0xbfb8aa3b, v11
	v_exp_f32_e32 v16, v16
	v_exp_f32_e32 v17, v17
	v_rcp_f32_e32 v14, v14
	v_rcp_f32_e32 v15, v15
	v_add_f32_e32 v16, 1.0, v16
	v_add_f32_e32 v17, 1.0, v17
	v_rcp_f32_e32 v16, v16
	v_rcp_f32_e32 v17, v17
	v_pk_mul_f32 v[8:9], v[8:9], v[14:15]
	v_pk_mul_f32 v[6:7], v[12:13], v[6:7]
	v_pk_mul_f32 v[8:9], v[8:9], v[0:1]
	v_pk_mul_f32 v[0:1], v[10:11], v[16:17]
	s_nop 0
	v_pk_mul_f32 v[10:11], v[0:1], v[2:3]
	v_cvt_pk_bf16_f32 v0, v4, v5
	v_mad_i64_i32 v[4:5], s[14:15], v18, s47, v[112:113]
	v_cvt_pk_bf16_f32 v1, v6, v7
	v_cvt_pk_bf16_f32 v2, v8, v9
	v_cvt_pk_bf16_f32 v3, v10, v11
	v_lshl_add_u64 v[4:5], v[4:5], 0, v[114:115]
	global_store_dwordx4 v[4:5], v[0:3], off nt
	s_cbranch_vccnz .LBB0_759
	s_andn2_b64 vcc, exec, s[0:1]
	s_cbranch_vccnz .LBB0_758
	s_barrier
	s_branch .LBB0_758

; DI float silu_f(float x) { return x * __builtin_amdgcn_rcpf(1.f + __expf(-x)); }
; #define EPI_LOOP_ROWS _Pragma("unroll") for (int ai = 0; ai < 2; ++ai) _Pragma("unroll") for (int m = 0; m < 4; ++m)
; DI u32x4 pack8(const f32x4 a, const f32x4 b) { return (u32x4){pack2(a[0], a[1]), pack2(a[2], a[3]), pack2(b[0], b[1]), pack2(b[2], b[3])}; }
;     DI void operator()(const AccT& acc, int brow, int bcol, int wr, int wc, int fr, int fq) const {
;         const int col = (bcol >> 1) + wc * 32 + fq * 8;
;         EPI_LOOP_ROWS { const size_t row = brow + ai * 128 + wr * 64 + m * 16 + fr; f32x4 o[2];
; #pragma unroll
;             for (int n = 0; n < 2; ++n) { const f32x4 g = acc[ai][0][m][n], u = acc[ai][1][m][n];
; #pragma unroll
;                 for (int j = 0; j < 4; ++j) o[n][j] = silu_f(g[j]) * u[j]; }
;             *(u32x4*)(ACT + row * DFF + col) = pack8(o[0], o[1]); }
;     }
.LBB0_1697:
	v_mov_b32_e32 v144, v252
	s_ashr_i32 s9, s36, 1
	v_lshrrev_b32_e32 v146, 1, v144
	v_and_b32_e32 v147, 0x60, v146
	v_and_b32_e32 v146, 24, v146
	v_add3_u32 v146, v147, s9, v146
	v_mul_f32_e32 v147, 0xbfb8aa3b, v124
	v_exp_f32_e32 v147, v147
	v_mul_f32_e32 v148, 0xbfb8aa3b, v125
	v_exp_f32_e32 v149, v148
	v_and_b32_e32 v145, 15, v144
	v_add_f32_e32 v147, 1.0, v147
	v_rcp_f32_e32 v148, v147
	v_add_f32_e32 v147, 1.0, v149
	v_rcp_f32_e32 v149, v147
	v_ashrrev_i32_e32 v144, 2, v144
	v_and_b32_e32 v144, 0xffffffc0, v144
	v_add3_u32 v144, v145, s34, v144
	v_pk_mul_f32 v[124:125], v[124:125], v[148:149]
	v_mul_f32_e32 v145, 0xbfb8aa3b, v126
	v_mul_f32_e32 v148, 0xbfb8aa3b, v127
	v_exp_f32_e32 v145, v145
	v_exp_f32_e32 v148, v148
	v_pk_mul_f32 v[116:117], v[124:125], v[116:117]
	v_ashrrev_i32_e32 v147, 31, v146
	v_add_f32_e32 v124, 1.0, v145
	v_add_f32_e32 v125, 1.0, v148
	v_mul_f32_e32 v145, 0xbfb8aa3b, v120
	v_rcp_f32_e32 v124, v124
	v_rcp_f32_e32 v125, v125
	v_exp_f32_e32 v145, v145
	v_mul_f32_e32 v148, 0xbfb8aa3b, v121
	v_exp_f32_e32 v148, v148
	v_pk_mul_f32 v[124:125], v[126:127], v[124:125]
	v_add_f32_e32 v126, 1.0, v145
	v_mul_f32_e32 v145, 0xbfb8aa3b, v122
	v_add_f32_e32 v127, 1.0, v148
	v_exp_f32_e32 v145, v145
	v_mul_f32_e32 v148, 0xbfb8aa3b, v123
	v_exp_f32_e32 v149, v148
	v_rcp_f32_e32 v126, v126
	v_add_f32_e32 v145, 1.0, v145
	v_rcp_f32_e32 v127, v127
	v_rcp_f32_e32 v148, v145
	v_add_f32_e32 v145, 1.0, v149
	v_rcp_f32_e32 v149, v145
	v_pk_mul_f32 v[120:121], v[120:121], v[126:127]
	v_pk_mul_f32 v[118:119], v[124:125], v[118:119]
	v_pk_mul_f32 v[112:113], v[120:121], v[112:113]
	v_pk_mul_f32 v[120:121], v[122:123], v[148:149]
	v_cvt_pk_bf16_f32 v116, v116, v117
	v_pk_mul_f32 v[114:115], v[120:121], v[114:115]
	v_cvt_pk_bf16_f32 v117, v118, v119
	v_cvt_pk_bf16_f32 v119, v114, v115
	v_mul_f32_e32 v114, 0xbfb8aa3b, v108
	v_exp_f32_e32 v122, v114
	v_mul_f32_e32 v114, 0xbfb8aa3b, v109
	v_exp_f32_e32 v123, v114
	v_cvt_pk_bf16_f32 v118, v112, v113
	v_mov_b64_e32 v[112:113], s[96:97]
	v_mad_i64_i32 v[120:121], s[14:15], v144, s50, v[112:113]
	v_lshlrev_b64 v[114:115], 1, v[146:147]
	v_add_f32_e32 v122, 1.0, v122
	v_add_f32_e32 v123, 1.0, v123
	v_lshl_add_u64 v[120:121], v[120:121], 0, v[114:115]
	v_rcp_f32_e32 v122, v122
	v_rcp_f32_e32 v123, v123
	global_store_dwordx4 v[120:121], v[116:119], off nt
	s_andn2_b64 vcc, exec, s[6:7]
	s_mov_b64 s[6:7], -1
	v_mul_f32_e32 v116, 0xbfb8aa3b, v110
	v_mul_f32_e32 v117, 0xbfb8aa3b, v111
	v_exp_f32_e32 v116, v116
	v_exp_f32_e32 v117, v117
	v_pk_mul_f32 v[108:109], v[108:109], v[122:123]
	v_add_u32_e32 v118, 16, v144
	v_pk_mul_f32 v[100:101], v[108:109], v[100:101]
	v_add_f32_e32 v108, 1.0, v116
	v_add_f32_e32 v109, 1.0, v117
	v_mul_f32_e32 v116, 0xbfb8aa3b, v104
	v_mul_f32_e32 v117, 0xbfb8aa3b, v105
	v_rcp_f32_e32 v108, v108
	v_rcp_f32_e32 v109, v109
	v_exp_f32_e32 v116, v116
	v_exp_f32_e32 v117, v117
	v_pk_mul_f32 v[108:109], v[110:111], v[108:109]
	v_add_f32_e32 v110, 1.0, v116
	v_add_f32_e32 v111, 1.0, v117
	v_mul_f32_e32 v116, 0xbfb8aa3b, v106
	v_mul_f32_e32 v117, 0xbfb8aa3b, v107
	v_exp_f32_e32 v116, v116
	v_exp_f32_e32 v117, v117
	v_rcp_f32_e32 v110, v110
	v_rcp_f32_e32 v111, v111
	v_add_f32_e32 v116, 1.0, v116
	v_add_f32_e32 v117, 1.0, v117
	v_rcp_f32_e32 v116, v116
	v_rcp_f32_e32 v117, v117
	v_pk_mul_f32 v[104:105], v[104:105], v[110:111]
	v_pk_mul_f32 v[102:103], v[108:109], v[102:103]
	v_pk_mul_f32 v[104:105], v[104:105], v[96:97]
	v_pk_mul_f32 v[96:97], v[106:107], v[116:117]
	s_nop 0
	v_pk_mul_f32 v[106:107], v[96:97], v[98:99]
	v_cvt_pk_bf16_f32 v96, v100, v101
	v_mul_f32_e32 v100, 0xbfb8aa3b, v92
	v_cvt_pk_bf16_f32 v97, v102, v103
	v_exp_f32_e32 v102, v100
	v_mul_f32_e32 v100, 0xbfb8aa3b, v93
	v_exp_f32_e32 v103, v100
	v_mad_i64_i32 v[100:101], s[14:15], v118, s50, v[112:113]
	v_cvt_pk_bf16_f32 v98, v104, v105
	v_cvt_pk_bf16_f32 v99, v106, v107
	v_add_f32_e32 v102, 1.0, v102
	v_add_f32_e32 v103, 1.0, v103
	v_lshl_add_u64 v[100:101], v[100:101], 0, v[114:115]
	v_rcp_f32_e32 v102, v102
	v_rcp_f32_e32 v103, v103
	global_store_dwordx4 v[100:101], v[96:99], off nt
	v_pk_mul_f32 v[92:93], v[92:93], v[102:103]
	s_nop 0
	v_mul_f32_e32 v96, 0xbfb8aa3b, v94
	v_mul_f32_e32 v97, 0xbfb8aa3b, v95
	v_exp_f32_e32 v96, v96
	v_exp_f32_e32 v97, v97
	v_pk_mul_f32 v[84:85], v[92:93], v[84:85]
	v_add_u32_e32 v98, 32, v144
	v_add_f32_e32 v92, 1.0, v96
	v_add_f32_e32 v93, 1.0, v97
	v_mul_f32_e32 v96, 0xbfb8aa3b, v88
	v_mul_f32_e32 v97, 0xbfb8aa3b, v89
	v_rcp_f32_e32 v92, v92
	v_rcp_f32_e32 v93, v93
	v_exp_f32_e32 v96, v96
	v_exp_f32_e32 v97, v97
	v_pk_mul_f32 v[92:93], v[94:95], v[92:93]
	v_add_f32_e32 v94, 1.0, v96
	v_add_f32_e32 v95, 1.0, v97
	v_mul_f32_e32 v96, 0xbfb8aa3b, v90
	v_mul_f32_e32 v97, 0xbfb8aa3b, v91
	v_exp_f32_e32 v96, v96
	v_exp_f32_e32 v97, v97
	v_rcp_f32_e32 v94, v94
	v_rcp_f32_e32 v95, v95
	v_add_f32_e32 v96, 1.0, v96
	v_add_f32_e32 v97, 1.0, v97
	v_rcp_f32_e32 v96, v96
	v_rcp_f32_e32 v97, v97
	v_pk_mul_f32 v[88:89], v[88:89], v[94:95]
	v_pk_mul_f32 v[86:87], v[92:93], v[86:87]
	v_pk_mul_f32 v[88:89], v[88:89], v[80:81]
	v_pk_mul_f32 v[80:81], v[90:91], v[96:97]
	s_nop 0
	v_pk_mul_f32 v[90:91], v[80:81], v[82:83]
	v_cvt_pk_bf16_f32 v80, v84, v85
	v_mul_f32_e32 v84, 0xbfb8aa3b, v76
	v_cvt_pk_bf16_f32 v81, v86, v87
	v_exp_f32_e32 v86, v84
	v_mul_f32_e32 v84, 0xbfb8aa3b, v77
	v_exp_f32_e32 v87, v84
	v_mad_i64_i32 v[84:85], s[14:15], v98, s50, v[112:113]
	v_cvt_pk_bf16_f32 v82, v88, v89
	v_cvt_pk_bf16_f32 v83, v90, v91
	v_add_f32_e32 v86, 1.0, v86
	v_add_f32_e32 v87, 1.0, v87
	v_lshl_add_u64 v[84:85], v[84:85], 0, v[114:115]
	v_rcp_f32_e32 v86, v86
	v_rcp_f32_e32 v87, v87
; DI float silu_f(float x) { return x * __builtin_amdgcn_rcpf(1.f + __expf(-x)); }
; #define EPI_LOOP_ROWS _Pragma("unroll") for (int ai = 0; ai < 2; ++ai) _Pragma("unroll") for (int m = 0; m < 4; ++m)
; DI u32x4 pack8(const f32x4 a, const f32x4 b) { return (u32x4){pack2(a[0], a[1]), pack2(a[2], a[3]), pack2(b[0], b[1]), pack2(b[2], b[3])}; }
;     DI void operator()(const AccT& acc, int brow, int bcol, int wr, int wc, int fr, int fq) const {
;         const int col = (bcol >> 1) + wc * 32 + fq * 8;
;         EPI_LOOP_ROWS { const size_t row = brow + ai * 128 + wr * 64 + m * 16 + fr; f32x4 o[2];
; #pragma unroll
;             for (int n = 0; n < 2; ++n) { const f32x4 g = acc[ai][0][m][n], u = acc[ai][1][m][n];
; #pragma unroll
;                 for (int j = 0; j < 4; ++j) o[n][j] = silu_f(g[j]) * u[j]; }
;             *(u32x4*)(ACT + row * DFF + col) = pack8(o[0], o[1]); }
;     }
	global_store_dwordx4 v[84:85], v[80:83], off nt
	v_pk_mul_f32 v[76:77], v[76:77], v[86:87]
	s_nop 0
	v_mul_f32_e32 v80, 0xbfb8aa3b, v78
	v_mul_f32_e32 v81, 0xbfb8aa3b, v79
	v_exp_f32_e32 v80, v80
	v_exp_f32_e32 v81, v81
	v_pk_mul_f32 v[68:69], v[76:77], v[68:69]
	v_add_u32_e32 v82, 48, v144
	v_add_f32_e32 v76, 1.0, v80
	v_add_f32_e32 v77, 1.0, v81
	v_mul_f32_e32 v80, 0xbfb8aa3b, v72
	v_mul_f32_e32 v81, 0xbfb8aa3b, v73
	v_rcp_f32_e32 v76, v76
	v_rcp_f32_e32 v77, v77
	v_exp_f32_e32 v80, v80
	v_exp_f32_e32 v81, v81
	v_pk_mul_f32 v[76:77], v[78:79], v[76:77]
	v_add_f32_e32 v78, 1.0, v80
	v_add_f32_e32 v79, 1.0, v81
	v_mul_f32_e32 v80, 0xbfb8aa3b, v74
	v_mul_f32_e32 v81, 0xbfb8aa3b, v75
	v_exp_f32_e32 v80, v80
	v_exp_f32_e32 v81, v81
	v_rcp_f32_e32 v78, v78
	v_rcp_f32_e32 v79, v79
	v_add_f32_e32 v80, 1.0, v80
	v_add_f32_e32 v81, 1.0, v81
	v_rcp_f32_e32 v80, v80
	v_rcp_f32_e32 v81, v81
	v_pk_mul_f32 v[72:73], v[72:73], v[78:79]
	v_pk_mul_f32 v[70:71], v[76:77], v[70:71]
	v_pk_mul_f32 v[72:73], v[72:73], v[64:65]
	v_pk_mul_f32 v[64:65], v[74:75], v[80:81]
	s_nop 0
	v_pk_mul_f32 v[74:75], v[64:65], v[66:67]
	v_cvt_pk_bf16_f32 v64, v68, v69
	v_mul_f32_e32 v68, 0xbfb8aa3b, v60
	v_cvt_pk_bf16_f32 v65, v70, v71
	v_exp_f32_e32 v70, v68
	v_mul_f32_e32 v68, 0xbfb8aa3b, v61
	v_exp_f32_e32 v71, v68
	v_mad_i64_i32 v[68:69], s[14:15], v82, s50, v[112:113]
	v_cvt_pk_bf16_f32 v66, v72, v73
	v_cvt_pk_bf16_f32 v67, v74, v75
	v_add_f32_e32 v70, 1.0, v70
	v_add_f32_e32 v71, 1.0, v71
	v_lshl_add_u64 v[68:69], v[68:69], 0, v[114:115]
	v_rcp_f32_e32 v70, v70
	v_rcp_f32_e32 v71, v71
	global_store_dwordx4 v[68:69], v[64:67], off nt
	v_pk_mul_f32 v[60:61], v[60:61], v[70:71]
	s_nop 0
	v_mul_f32_e32 v64, 0xbfb8aa3b, v62
	v_mul_f32_e32 v65, 0xbfb8aa3b, v63
	v_exp_f32_e32 v64, v64
	v_exp_f32_e32 v65, v65
	v_pk_mul_f32 v[52:53], v[60:61], v[52:53]
	v_add_u32_e32 v66, 0x80, v144
	v_add_f32_e32 v60, 1.0, v64
	v_add_f32_e32 v61, 1.0, v65
	v_mul_f32_e32 v64, 0xbfb8aa3b, v56
	v_mul_f32_e32 v65, 0xbfb8aa3b, v57
	v_rcp_f32_e32 v60, v60
	v_rcp_f32_e32 v61, v61
	v_exp_f32_e32 v64, v64
	v_exp_f32_e32 v65, v65
	v_pk_mul_f32 v[60:61], v[62:63], v[60:61]
	v_add_f32_e32 v62, 1.0, v64
	v_add_f32_e32 v63, 1.0, v65
	v_mul_f32_e32 v64, 0xbfb8aa3b, v58
	v_mul_f32_e32 v65, 0xbfb8aa3b, v59
	v_exp_f32_e32 v64, v64
	v_exp_f32_e32 v65, v65
	v_rcp_f32_e32 v62, v62
	v_rcp_f32_e32 v63, v63
	v_add_f32_e32 v64, 1.0, v64
	v_add_f32_e32 v65, 1.0, v65
	v_rcp_f32_e32 v64, v64
	v_rcp_f32_e32 v65, v65
	v_pk_mul_f32 v[56:57], v[56:57], v[62:63]
	v_pk_mul_f32 v[54:55], v[60:61], v[54:55]
	v_pk_mul_f32 v[56:57], v[56:57], v[48:49]
	v_pk_mul_f32 v[48:49], v[58:59], v[64:65]
	s_nop 0
	v_pk_mul_f32 v[58:59], v[48:49], v[50:51]
	v_cvt_pk_bf16_f32 v48, v52, v53
	v_mul_f32_e32 v52, 0xbfb8aa3b, v44
	v_cvt_pk_bf16_f32 v49, v54, v55
	v_exp_f32_e32 v54, v52
	v_mul_f32_e32 v52, 0xbfb8aa3b, v45
	v_exp_f32_e32 v55, v52
	v_mad_i64_i32 v[52:53], s[14:15], v66, s50, v[112:113]
	v_cvt_pk_bf16_f32 v50, v56, v57
	v_cvt_pk_bf16_f32 v51, v58, v59
	v_add_f32_e32 v54, 1.0, v54
	v_add_f32_e32 v55, 1.0, v55
	v_lshl_add_u64 v[52:53], v[52:53], 0, v[114:115]
	v_rcp_f32_e32 v54, v54
	v_rcp_f32_e32 v55, v55
	global_store_dwordx4 v[52:53], v[48:51], off nt
	v_pk_mul_f32 v[44:45], v[44:45], v[54:55]
	s_nop 0
	v_mul_f32_e32 v48, 0xbfb8aa3b, v46
	v_mul_f32_e32 v49, 0xbfb8aa3b, v47
	v_exp_f32_e32 v48, v48
	v_exp_f32_e32 v49, v49
	v_pk_mul_f32 v[36:37], v[44:45], v[36:37]
	v_add_u32_e32 v50, 0x90, v144
	v_add_f32_e32 v44, 1.0, v48
	v_add_f32_e32 v45, 1.0, v49
	v_mul_f32_e32 v48, 0xbfb8aa3b, v40
	v_mul_f32_e32 v49, 0xbfb8aa3b, v41
	v_rcp_f32_e32 v44, v44
	v_rcp_f32_e32 v45, v45
	v_exp_f32_e32 v48, v48
	v_exp_f32_e32 v49, v49
	v_pk_mul_f32 v[44:45], v[46:47], v[44:45]
	v_add_f32_e32 v46, 1.0, v48
	v_add_f32_e32 v47, 1.0, v49
	v_mul_f32_e32 v48, 0xbfb8aa3b, v42
	v_mul_f32_e32 v49, 0xbfb8aa3b, v43
	v_exp_f32_e32 v48, v48
	v_exp_f32_e32 v49, v49
; DI float silu_f(float x) { return x * __builtin_amdgcn_rcpf(1.f + __expf(-x)); }
; #define BAR __builtin_amdgcn_s_barrier()
; #define EPI_LOOP_ROWS _Pragma("unroll") for (int ai = 0; ai < 2; ++ai) _Pragma("unroll") for (int m = 0; m < 4; ++m)
; DI u32x4 pack8(const f32x4 a, const f32x4 b) { return (u32x4){pack2(a[0], a[1]), pack2(a[2], a[3]), pack2(b[0], b[1]), pack2(b[2], b[3])}; }
; template <class Get, class Epi>
; DI void gemm_loop(int ntiles, int ld, char* shm, const Get& get, const Epi& epi) {
;     ...
;         if (wr == 0) BAR;
;         { int tx2 = threadIdx.x, brow2 = cur.brow, bcol2 = cur.bcol, Lo = L; asm volatile("" : "+v"(tx2), "+s"(brow2), "+s"(bcol2), "+s"(Lo));
;           const int wid2 = tx2 >> 6, lane2 = tx2 & 63; epi(Lo, acc, brow2, bcol2, wid2 >> 2, wid2 & 3, lane2 & 15, lane2 >> 4); }
;         if (!has_next) break;
;         G_ZERO;
;         cur = nxt; cA = nA; cB = nB; L = Ln;
;         if (wr == 1) BAR;
;     DI void operator()(const AccT& acc, int brow, int bcol, int wr, int wc, int fr, int fq) const {
;         const int col = (bcol >> 1) + wc * 32 + fq * 8;
;         EPI_LOOP_ROWS { const size_t row = brow + ai * 128 + wr * 64 + m * 16 + fr; f32x4 o[2];
; #pragma unroll
;             for (int n = 0; n < 2; ++n) { const f32x4 g = acc[ai][0][m][n], u = acc[ai][1][m][n];
; #pragma unroll
;                 for (int j = 0; j < 4; ++j) o[n][j] = silu_f(g[j]) * u[j]; }
;             *(u32x4*)(ACT + row * DFF + col) = pack8(o[0], o[1]); }
;     }
	v_rcp_f32_e32 v46, v46
	v_rcp_f32_e32 v47, v47
	v_add_f32_e32 v48, 1.0, v48
	v_add_f32_e32 v49, 1.0, v49
	v_rcp_f32_e32 v48, v48
	v_rcp_f32_e32 v49, v49
	v_pk_mul_f32 v[40:41], v[40:41], v[46:47]
	v_pk_mul_f32 v[38:39], v[44:45], v[38:39]
	v_pk_mul_f32 v[40:41], v[40:41], v[32:33]
	v_pk_mul_f32 v[32:33], v[42:43], v[48:49]
	s_nop 0
	v_pk_mul_f32 v[42:43], v[32:33], v[34:35]
	v_cvt_pk_bf16_f32 v32, v36, v37
	v_mul_f32_e32 v36, 0xbfb8aa3b, v28
	v_cvt_pk_bf16_f32 v33, v38, v39
	v_exp_f32_e32 v38, v36
	v_mul_f32_e32 v36, 0xbfb8aa3b, v29
	v_exp_f32_e32 v39, v36
	v_mad_i64_i32 v[36:37], s[14:15], v50, s50, v[112:113]
	v_cvt_pk_bf16_f32 v34, v40, v41
	v_cvt_pk_bf16_f32 v35, v42, v43
	v_add_f32_e32 v38, 1.0, v38
	v_add_f32_e32 v39, 1.0, v39
	v_lshl_add_u64 v[36:37], v[36:37], 0, v[114:115]
	v_rcp_f32_e32 v38, v38
	v_rcp_f32_e32 v39, v39
	global_store_dwordx4 v[36:37], v[32:35], off nt
	v_pk_mul_f32 v[28:29], v[28:29], v[38:39]
	s_nop 0
	v_mul_f32_e32 v32, 0xbfb8aa3b, v30
	v_mul_f32_e32 v33, 0xbfb8aa3b, v31
	v_exp_f32_e32 v32, v32
	v_exp_f32_e32 v33, v33
	v_pk_mul_f32 v[20:21], v[28:29], v[20:21]
	v_add_u32_e32 v34, 0xa0, v144
	v_add_f32_e32 v28, 1.0, v32
	v_add_f32_e32 v29, 1.0, v33
	v_mul_f32_e32 v32, 0xbfb8aa3b, v24
	v_mul_f32_e32 v33, 0xbfb8aa3b, v25
	v_rcp_f32_e32 v28, v28
	v_rcp_f32_e32 v29, v29
	v_exp_f32_e32 v32, v32
	v_exp_f32_e32 v33, v33
	v_pk_mul_f32 v[28:29], v[30:31], v[28:29]
	v_add_f32_e32 v30, 1.0, v32
	v_add_f32_e32 v31, 1.0, v33
	v_mul_f32_e32 v32, 0xbfb8aa3b, v26
	v_mul_f32_e32 v33, 0xbfb8aa3b, v27
	v_exp_f32_e32 v32, v32
	v_exp_f32_e32 v33, v33
	v_rcp_f32_e32 v30, v30
	v_rcp_f32_e32 v31, v31
	v_add_f32_e32 v32, 1.0, v32
	v_add_f32_e32 v33, 1.0, v33
	v_rcp_f32_e32 v32, v32
	v_rcp_f32_e32 v33, v33
	v_pk_mul_f32 v[24:25], v[24:25], v[30:31]
	v_pk_mul_f32 v[22:23], v[28:29], v[22:23]
	v_pk_mul_f32 v[24:25], v[24:25], v[16:17]
	v_pk_mul_f32 v[16:17], v[26:27], v[32:33]
	s_nop 0
	v_pk_mul_f32 v[26:27], v[16:17], v[18:19]
	v_cvt_pk_bf16_f32 v16, v20, v21
	v_mul_f32_e32 v20, 0xbfb8aa3b, v12
	v_cvt_pk_bf16_f32 v17, v22, v23
	v_exp_f32_e32 v22, v20
	v_mul_f32_e32 v20, 0xbfb8aa3b, v13
	v_exp_f32_e32 v23, v20
	v_mad_i64_i32 v[20:21], s[14:15], v34, s50, v[112:113]
	v_cvt_pk_bf16_f32 v18, v24, v25
	v_cvt_pk_bf16_f32 v19, v26, v27
	v_add_f32_e32 v22, 1.0, v22
	v_add_f32_e32 v23, 1.0, v23
	v_lshl_add_u64 v[20:21], v[20:21], 0, v[114:115]
	v_rcp_f32_e32 v22, v22
	v_rcp_f32_e32 v23, v23
	global_store_dwordx4 v[20:21], v[16:19], off nt
	v_pk_mul_f32 v[12:13], v[12:13], v[22:23]
	s_nop 0
	v_mul_f32_e32 v16, 0xbfb8aa3b, v14
	v_mul_f32_e32 v17, 0xbfb8aa3b, v15
	v_exp_f32_e32 v16, v16
	v_exp_f32_e32 v17, v17
	v_pk_mul_f32 v[4:5], v[12:13], v[4:5]
	v_add_u32_e32 v18, 0xb0, v144
	v_add_f32_e32 v12, 1.0, v16
	v_add_f32_e32 v13, 1.0, v17
	v_mul_f32_e32 v16, 0xbfb8aa3b, v8
	v_mul_f32_e32 v17, 0xbfb8aa3b, v9
	v_rcp_f32_e32 v12, v12
	v_rcp_f32_e32 v13, v13
	v_exp_f32_e32 v16, v16
	v_exp_f32_e32 v17, v17
	v_pk_mul_f32 v[12:13], v[14:15], v[12:13]
	v_add_f32_e32 v14, 1.0, v16
	v_add_f32_e32 v15, 1.0, v17
	v_mul_f32_e32 v16, 0xbfb8aa3b, v10
	v_mul_f32_e32 v17, 0xbfb8aa3b, v11
	v_exp_f32_e32 v16, v16
	v_exp_f32_e32 v17, v17
	v_rcp_f32_e32 v14, v14
	v_rcp_f32_e32 v15, v15
	v_add_f32_e32 v16, 1.0, v16
	v_add_f32_e32 v17, 1.0, v17
	v_rcp_f32_e32 v16, v16
	v_rcp_f32_e32 v17, v17
	v_pk_mul_f32 v[8:9], v[8:9], v[14:15]
	v_pk_mul_f32 v[6:7], v[12:13], v[6:7]
	v_pk_mul_f32 v[8:9], v[8:9], v[0:1]
	v_pk_mul_f32 v[0:1], v[10:11], v[16:17]
	s_nop 0
	v_pk_mul_f32 v[10:11], v[0:1], v[2:3]
	v_cvt_pk_bf16_f32 v0, v4, v5
	v_mad_i64_i32 v[4:5], s[14:15], v18, s50, v[112:113]
	v_cvt_pk_bf16_f32 v1, v6, v7
	v_cvt_pk_bf16_f32 v2, v8, v9
	v_cvt_pk_bf16_f32 v3, v10, v11
	v_lshl_add_u64 v[4:5], v[4:5], 0, v[114:115]
	global_store_dwordx4 v[4:5], v[0:3], off nt
	s_cbranch_vccnz .LBB0_1690
	s_andn2_b64 vcc, exec, s[0:1]
	s_cbranch_vccnz .LBB0_1689
	s_barrier
	s_branch .LBB0_1689

; #define EPI_LOOP_ROWS _Pragma("unroll") for (int ai = 0; ai < 2; ++ai) _Pragma("unroll") for (int m = 0; m < 4; ++m)
; DI u32x4 pack8(const f32x4 a, const f32x4 b) { return (u32x4){pack2(a[0], a[1]), pack2(a[2], a[3]), pack2(b[0], b[1]), pack2(b[2], b[3])}; }
; DI float silu_f(float x) { return x * __builtin_amdgcn_rcpf(1.f + __expf(-x)); }
;     DI void operator()(const AccT& acc, int brow, int bcol, int wr, int wc, int fr, int fq) const {
;         const int col = (bcol >> 1) + wc * 32 + fq * 8;
;         EPI_LOOP_ROWS { const size_t row = brow + ai * 128 + wr * 64 + m * 16 + fr; f32x4 o[2];
; #pragma unroll
;             for (int n = 0; n < 2; ++n) { const f32x4 g = acc[ai][0][m][n], u = acc[ai][1][m][n];
; #pragma unroll
;                 for (int j = 0; j < 4; ++j) o[n][j] = silu_f(g[j]) * u[j]; }
;             *(u32x4*)(ACT + row * DFF + col) = pack8(o[0], o[1]); }
;     }
.LBB0_3682:
	v_mov_b32_e32 v144, v252
	s_ashr_i32 s9, s30, 1
	v_lshrrev_b32_e32 v146, 1, v144
	v_and_b32_e32 v147, 0x60, v146
	v_and_b32_e32 v146, 24, v146
	v_add3_u32 v146, v147, s9, v146
	v_mul_f32_e32 v147, 0xbfb8aa3b, v124
	v_exp_f32_e32 v147, v147
	v_mul_f32_e32 v148, 0xbfb8aa3b, v125
	v_exp_f32_e32 v149, v148
	v_and_b32_e32 v145, 15, v144
	v_add_f32_e32 v147, 1.0, v147
	v_rcp_f32_e32 v148, v147
	v_add_f32_e32 v147, 1.0, v149
	v_rcp_f32_e32 v149, v147
	v_ashrrev_i32_e32 v144, 2, v144
	v_and_b32_e32 v144, 0xffffffc0, v144
	v_add3_u32 v144, v145, s24, v144
	v_pk_mul_f32 v[124:125], v[124:125], v[148:149]
	v_mul_f32_e32 v145, 0xbfb8aa3b, v126
	v_mul_f32_e32 v148, 0xbfb8aa3b, v127
	v_exp_f32_e32 v145, v145
	v_exp_f32_e32 v148, v148
	v_pk_mul_f32 v[116:117], v[124:125], v[116:117]
	v_ashrrev_i32_e32 v147, 31, v146
	v_add_f32_e32 v124, 1.0, v145
	v_add_f32_e32 v125, 1.0, v148
	v_mul_f32_e32 v145, 0xbfb8aa3b, v120
	v_rcp_f32_e32 v124, v124
	v_rcp_f32_e32 v125, v125
	v_exp_f32_e32 v145, v145
	v_mul_f32_e32 v148, 0xbfb8aa3b, v121
	v_exp_f32_e32 v148, v148
	v_pk_mul_f32 v[124:125], v[126:127], v[124:125]
	v_add_f32_e32 v126, 1.0, v145
	v_mul_f32_e32 v145, 0xbfb8aa3b, v122
	v_add_f32_e32 v127, 1.0, v148
	v_exp_f32_e32 v145, v145
	v_mul_f32_e32 v148, 0xbfb8aa3b, v123
	v_exp_f32_e32 v149, v148
	v_rcp_f32_e32 v126, v126
	v_add_f32_e32 v145, 1.0, v145
	v_rcp_f32_e32 v127, v127
	v_rcp_f32_e32 v148, v145
	v_add_f32_e32 v145, 1.0, v149
	v_rcp_f32_e32 v149, v145
	v_pk_mul_f32 v[120:121], v[120:121], v[126:127]
	v_pk_mul_f32 v[118:119], v[124:125], v[118:119]
	v_pk_mul_f32 v[112:113], v[120:121], v[112:113]
	v_pk_mul_f32 v[120:121], v[122:123], v[148:149]
	v_cvt_pk_bf16_f32 v116, v116, v117
	v_pk_mul_f32 v[114:115], v[120:121], v[114:115]
	v_cvt_pk_bf16_f32 v117, v118, v119
	v_cvt_pk_bf16_f32 v119, v114, v115
	v_mul_f32_e32 v114, 0xbfb8aa3b, v108
	v_exp_f32_e32 v122, v114
	v_mul_f32_e32 v114, 0xbfb8aa3b, v109
	v_exp_f32_e32 v123, v114
	v_cvt_pk_bf16_f32 v118, v112, v113
	v_mov_b64_e32 v[112:113], s[96:97]
	v_mad_i64_i32 v[120:121], s[14:15], v144, s46, v[112:113]
	v_lshlrev_b64 v[114:115], 1, v[146:147]
	v_add_f32_e32 v122, 1.0, v122
	v_add_f32_e32 v123, 1.0, v123
	v_lshl_add_u64 v[120:121], v[120:121], 0, v[114:115]
	v_rcp_f32_e32 v122, v122
	v_rcp_f32_e32 v123, v123
	global_store_dwordx4 v[120:121], v[116:119], off nt
	s_andn2_b64 vcc, exec, s[6:7]
	s_mov_b64 s[6:7], -1
	v_mul_f32_e32 v116, 0xbfb8aa3b, v110
	v_mul_f32_e32 v117, 0xbfb8aa3b, v111
	v_exp_f32_e32 v116, v116
	v_exp_f32_e32 v117, v117
	v_pk_mul_f32 v[108:109], v[108:109], v[122:123]
	v_add_u32_e32 v118, 16, v144
	v_pk_mul_f32 v[100:101], v[108:109], v[100:101]
	v_add_f32_e32 v108, 1.0, v116
	v_add_f32_e32 v109, 1.0, v117
	v_mul_f32_e32 v116, 0xbfb8aa3b, v104
	v_mul_f32_e32 v117, 0xbfb8aa3b, v105
	v_rcp_f32_e32 v108, v108
	v_rcp_f32_e32 v109, v109
	v_exp_f32_e32 v116, v116
	v_exp_f32_e32 v117, v117
	v_pk_mul_f32 v[108:109], v[110:111], v[108:109]
	v_add_f32_e32 v110, 1.0, v116
	v_add_f32_e32 v111, 1.0, v117
	v_mul_f32_e32 v116, 0xbfb8aa3b, v106
	v_mul_f32_e32 v117, 0xbfb8aa3b, v107
	v_exp_f32_e32 v116, v116
	v_exp_f32_e32 v117, v117
	v_rcp_f32_e32 v110, v110
	v_rcp_f32_e32 v111, v111
	v_add_f32_e32 v116, 1.0, v116
	v_add_f32_e32 v117, 1.0, v117
	v_rcp_f32_e32 v116, v116
	v_rcp_f32_e32 v117, v117
	v_pk_mul_f32 v[104:105], v[104:105], v[110:111]
	v_pk_mul_f32 v[102:103], v[108:109], v[102:103]
	v_pk_mul_f32 v[104:105], v[104:105], v[96:97]
	v_pk_mul_f32 v[96:97], v[106:107], v[116:117]
	s_nop 0
	v_pk_mul_f32 v[106:107], v[96:97], v[98:99]
	v_cvt_pk_bf16_f32 v96, v100, v101
	v_mul_f32_e32 v100, 0xbfb8aa3b, v92
	v_cvt_pk_bf16_f32 v97, v102, v103
	v_exp_f32_e32 v102, v100
	v_mul_f32_e32 v100, 0xbfb8aa3b, v93
	v_exp_f32_e32 v103, v100
	v_mad_i64_i32 v[100:101], s[14:15], v118, s46, v[112:113]
	v_cvt_pk_bf16_f32 v98, v104, v105
	v_cvt_pk_bf16_f32 v99, v106, v107
	v_add_f32_e32 v102, 1.0, v102
	v_add_f32_e32 v103, 1.0, v103
	v_lshl_add_u64 v[100:101], v[100:101], 0, v[114:115]
	v_rcp_f32_e32 v102, v102
	v_rcp_f32_e32 v103, v103
	global_store_dwordx4 v[100:101], v[96:99], off nt
	v_pk_mul_f32 v[92:93], v[92:93], v[102:103]
	s_nop 0
	v_mul_f32_e32 v96, 0xbfb8aa3b, v94
	v_mul_f32_e32 v97, 0xbfb8aa3b, v95
	v_exp_f32_e32 v96, v96
	v_exp_f32_e32 v97, v97
	v_pk_mul_f32 v[84:85], v[92:93], v[84:85]
	v_add_u32_e32 v98, 32, v144
	v_add_f32_e32 v92, 1.0, v96
	v_add_f32_e32 v93, 1.0, v97
	v_mul_f32_e32 v96, 0xbfb8aa3b, v88
	v_mul_f32_e32 v97, 0xbfb8aa3b, v89
	v_rcp_f32_e32 v92, v92
	v_rcp_f32_e32 v93, v93
	v_exp_f32_e32 v96, v96
	v_exp_f32_e32 v97, v97
	v_pk_mul_f32 v[92:93], v[94:95], v[92:93]
	v_add_f32_e32 v94, 1.0, v96
	v_add_f32_e32 v95, 1.0, v97
	v_mul_f32_e32 v96, 0xbfb8aa3b, v90
	v_mul_f32_e32 v97, 0xbfb8aa3b, v91
	v_exp_f32_e32 v96, v96
	v_exp_f32_e32 v97, v97
	v_rcp_f32_e32 v94, v94
	v_rcp_f32_e32 v95, v95
	v_add_f32_e32 v96, 1.0, v96
	v_add_f32_e32 v97, 1.0, v97
	v_rcp_f32_e32 v96, v96
	v_rcp_f32_e32 v97, v97
	v_pk_mul_f32 v[88:89], v[88:89], v[94:95]
	v_pk_mul_f32 v[86:87], v[92:93], v[86:87]
	v_pk_mul_f32 v[88:89], v[88:89], v[80:81]
	v_pk_mul_f32 v[80:81], v[90:91], v[96:97]
	s_nop 0
	v_pk_mul_f32 v[90:91], v[80:81], v[82:83]
	v_cvt_pk_bf16_f32 v80, v84, v85
	v_mul_f32_e32 v84, 0xbfb8aa3b, v76
	v_cvt_pk_bf16_f32 v81, v86, v87
	v_exp_f32_e32 v86, v84
	v_mul_f32_e32 v84, 0xbfb8aa3b, v77
	v_exp_f32_e32 v87, v84
	v_mad_i64_i32 v[84:85], s[14:15], v98, s46, v[112:113]
	v_cvt_pk_bf16_f32 v82, v88, v89
	v_cvt_pk_bf16_f32 v83, v90, v91
	v_add_f32_e32 v86, 1.0, v86
	v_add_f32_e32 v87, 1.0, v87
	v_lshl_add_u64 v[84:85], v[84:85], 0, v[114:115]
	v_rcp_f32_e32 v86, v86
	v_rcp_f32_e32 v87, v87
; #define EPI_LOOP_ROWS _Pragma("unroll") for (int ai = 0; ai < 2; ++ai) _Pragma("unroll") for (int m = 0; m < 4; ++m)
; DI u32x4 pack8(const f32x4 a, const f32x4 b) { return (u32x4){pack2(a[0], a[1]), pack2(a[2], a[3]), pack2(b[0], b[1]), pack2(b[2], b[3])}; }
; DI float silu_f(float x) { return x * __builtin_amdgcn_rcpf(1.f + __expf(-x)); }
;     DI void operator()(const AccT& acc, int brow, int bcol, int wr, int wc, int fr, int fq) const {
;         const int col = (bcol >> 1) + wc * 32 + fq * 8;
;         EPI_LOOP_ROWS { const size_t row = brow + ai * 128 + wr * 64 + m * 16 + fr; f32x4 o[2];
; #pragma unroll
;             for (int n = 0; n < 2; ++n) { const f32x4 g = acc[ai][0][m][n], u = acc[ai][1][m][n];
; #pragma unroll
;                 for (int j = 0; j < 4; ++j) o[n][j] = silu_f(g[j]) * u[j]; }
;             *(u32x4*)(ACT + row * DFF + col) = pack8(o[0], o[1]); }
	global_store_dwordx4 v[84:85], v[80:83], off nt
	v_pk_mul_f32 v[76:77], v[76:77], v[86:87]
	s_nop 0
	v_mul_f32_e32 v80, 0xbfb8aa3b, v78
	v_mul_f32_e32 v81, 0xbfb8aa3b, v79
	v_exp_f32_e32 v80, v80
	v_exp_f32_e32 v81, v81
	v_pk_mul_f32 v[68:69], v[76:77], v[68:69]
	v_add_u32_e32 v82, 48, v144
	v_add_f32_e32 v76, 1.0, v80
	v_add_f32_e32 v77, 1.0, v81
	v_mul_f32_e32 v80, 0xbfb8aa3b, v72
	v_mul_f32_e32 v81, 0xbfb8aa3b, v73
	v_rcp_f32_e32 v76, v76
	v_rcp_f32_e32 v77, v77
	v_exp_f32_e32 v80, v80
	v_exp_f32_e32 v81, v81
	v_pk_mul_f32 v[76:77], v[78:79], v[76:77]
	v_add_f32_e32 v78, 1.0, v80
	v_add_f32_e32 v79, 1.0, v81
	v_mul_f32_e32 v80, 0xbfb8aa3b, v74
	v_mul_f32_e32 v81, 0xbfb8aa3b, v75
	v_exp_f32_e32 v80, v80
	v_exp_f32_e32 v81, v81
	v_rcp_f32_e32 v78, v78
	v_rcp_f32_e32 v79, v79
	v_add_f32_e32 v80, 1.0, v80
	v_add_f32_e32 v81, 1.0, v81
	v_rcp_f32_e32 v80, v80
	v_rcp_f32_e32 v81, v81
	v_pk_mul_f32 v[72:73], v[72:73], v[78:79]
	v_pk_mul_f32 v[70:71], v[76:77], v[70:71]
	v_pk_mul_f32 v[72:73], v[72:73], v[64:65]
	v_pk_mul_f32 v[64:65], v[74:75], v[80:81]
	s_nop 0
	v_pk_mul_f32 v[74:75], v[64:65], v[66:67]
	v_cvt_pk_bf16_f32 v64, v68, v69
	v_mul_f32_e32 v68, 0xbfb8aa3b, v60
	v_cvt_pk_bf16_f32 v65, v70, v71
	v_exp_f32_e32 v70, v68
	v_mul_f32_e32 v68, 0xbfb8aa3b, v61
	v_exp_f32_e32 v71, v68
	v_mad_i64_i32 v[68:69], s[14:15], v82, s46, v[112:113]
	v_cvt_pk_bf16_f32 v66, v72, v73
	v_cvt_pk_bf16_f32 v67, v74, v75
	v_add_f32_e32 v70, 1.0, v70
	v_add_f32_e32 v71, 1.0, v71
	v_lshl_add_u64 v[68:69], v[68:69], 0, v[114:115]
	v_rcp_f32_e32 v70, v70
	v_rcp_f32_e32 v71, v71
	global_store_dwordx4 v[68:69], v[64:67], off nt
	v_pk_mul_f32 v[60:61], v[60:61], v[70:71]
	s_nop 0
	v_mul_f32_e32 v64, 0xbfb8aa3b, v62
	v_mul_f32_e32 v65, 0xbfb8aa3b, v63
	v_exp_f32_e32 v64, v64
	v_exp_f32_e32 v65, v65
	v_pk_mul_f32 v[52:53], v[60:61], v[52:53]
	v_add_u32_e32 v66, 0x80, v144
	v_add_f32_e32 v60, 1.0, v64
	v_add_f32_e32 v61, 1.0, v65
	v_mul_f32_e32 v64, 0xbfb8aa3b, v56
	v_mul_f32_e32 v65, 0xbfb8aa3b, v57
	v_rcp_f32_e32 v60, v60
	v_rcp_f32_e32 v61, v61
	v_exp_f32_e32 v64, v64
	v_exp_f32_e32 v65, v65
	v_pk_mul_f32 v[60:61], v[62:63], v[60:61]
	v_add_f32_e32 v62, 1.0, v64
	v_add_f32_e32 v63, 1.0, v65
	v_mul_f32_e32 v64, 0xbfb8aa3b, v58
	v_mul_f32_e32 v65, 0xbfb8aa3b, v59
	v_exp_f32_e32 v64, v64
	v_exp_f32_e32 v65, v65
	v_rcp_f32_e32 v62, v62
	v_rcp_f32_e32 v63, v63
	v_add_f32_e32 v64, 1.0, v64
	v_add_f32_e32 v65, 1.0, v65
	v_rcp_f32_e32 v64, v64
	v_rcp_f32_e32 v65, v65
	v_pk_mul_f32 v[56:57], v[56:57], v[62:63]
	v_pk_mul_f32 v[54:55], v[60:61], v[54:55]
	v_pk_mul_f32 v[56:57], v[56:57], v[48:49]
	v_pk_mul_f32 v[48:49], v[58:59], v[64:65]
	s_nop 0
	v_pk_mul_f32 v[58:59], v[48:49], v[50:51]
	v_cvt_pk_bf16_f32 v48, v52, v53
	v_mul_f32_e32 v52, 0xbfb8aa3b, v44
	v_cvt_pk_bf16_f32 v49, v54, v55
	v_exp_f32_e32 v54, v52
	v_mul_f32_e32 v52, 0xbfb8aa3b, v45
	v_exp_f32_e32 v55, v52
	v_mad_i64_i32 v[52:53], s[14:15], v66, s46, v[112:113]
	v_cvt_pk_bf16_f32 v50, v56, v57
	v_cvt_pk_bf16_f32 v51, v58, v59
	v_add_f32_e32 v54, 1.0, v54
	v_add_f32_e32 v55, 1.0, v55
	v_lshl_add_u64 v[52:53], v[52:53], 0, v[114:115]
	v_rcp_f32_e32 v54, v54
	v_rcp_f32_e32 v55, v55
	global_store_dwordx4 v[52:53], v[48:51], off nt
	v_pk_mul_f32 v[44:45], v[44:45], v[54:55]
	s_nop 0
	v_mul_f32_e32 v48, 0xbfb8aa3b, v46
	v_mul_f32_e32 v49, 0xbfb8aa3b, v47
	v_exp_f32_e32 v48, v48
	v_exp_f32_e32 v49, v49
	v_pk_mul_f32 v[36:37], v[44:45], v[36:37]
	v_add_u32_e32 v50, 0x90, v144
	v_add_f32_e32 v44, 1.0, v48
	v_add_f32_e32 v45, 1.0, v49
	v_mul_f32_e32 v48, 0xbfb8aa3b, v40
	v_mul_f32_e32 v49, 0xbfb8aa3b, v41
	v_rcp_f32_e32 v44, v44
	v_rcp_f32_e32 v45, v45
	v_exp_f32_e32 v48, v48
	v_exp_f32_e32 v49, v49
	v_pk_mul_f32 v[44:45], v[46:47], v[44:45]
	v_add_f32_e32 v46, 1.0, v48
	v_add_f32_e32 v47, 1.0, v49
	v_mul_f32_e32 v48, 0xbfb8aa3b, v42
	v_mul_f32_e32 v49, 0xbfb8aa3b, v43
	v_exp_f32_e32 v48, v48
	v_exp_f32_e32 v49, v49
; DI float silu_f(float x) { return x * __builtin_amdgcn_rcpf(1.f + __expf(-x)); }
; #define BAR __builtin_amdgcn_s_barrier()
; #define EPI_LOOP_ROWS _Pragma("unroll") for (int ai = 0; ai < 2; ++ai) _Pragma("unroll") for (int m = 0; m < 4; ++m)
; DI u32x4 pack8(const f32x4 a, const f32x4 b) { return (u32x4){pack2(a[0], a[1]), pack2(a[2], a[3]), pack2(b[0], b[1]), pack2(b[2], b[3])}; }
; template <class Get, class Epi>
; DI void gemm_loop(int ntiles, int ld, char* shm, const Get& get, const Epi& epi) {
;     ...
;         if (wr == 0) BAR;
;         { int tx2 = threadIdx.x, brow2 = cur.brow, bcol2 = cur.bcol, Lo = L; asm volatile("" : "+v"(tx2), "+s"(brow2), "+s"(bcol2), "+s"(Lo));
;           const int wid2 = tx2 >> 6, lane2 = tx2 & 63; epi(Lo, acc, brow2, bcol2, wid2 >> 2, wid2 & 3, lane2 & 15, lane2 >> 4); }
;         if (!has_next) break;
;         G_ZERO;
;         cur = nxt; cA = nA; cB = nB; L = Ln;
;         if (wr == 1) BAR;
;     DI void operator()(const AccT& acc, int brow, int bcol, int wr, int wc, int fr, int fq) const {
;         const int col = (bcol >> 1) + wc * 32 + fq * 8;
;         EPI_LOOP_ROWS { const size_t row = brow + ai * 128 + wr * 64 + m * 16 + fr; f32x4 o[2];
; #pragma unroll
;             for (int n = 0; n < 2; ++n) { const f32x4 g = acc[ai][0][m][n], u = acc[ai][1][m][n];
; #pragma unroll
;                 for (int j = 0; j < 4; ++j) o[n][j] = silu_f(g[j]) * u[j]; }
;             *(u32x4*)(ACT + row * DFF + col) = pack8(o[0], o[1]); }
;     }
	v_rcp_f32_e32 v46, v46
	v_rcp_f32_e32 v47, v47
	v_add_f32_e32 v48, 1.0, v48
	v_add_f32_e32 v49, 1.0, v49
	v_rcp_f32_e32 v48, v48
	v_rcp_f32_e32 v49, v49
	v_pk_mul_f32 v[40:41], v[40:41], v[46:47]
	v_pk_mul_f32 v[38:39], v[44:45], v[38:39]
	v_pk_mul_f32 v[40:41], v[40:41], v[32:33]
	v_pk_mul_f32 v[32:33], v[42:43], v[48:49]
	s_nop 0
	v_pk_mul_f32 v[42:43], v[32:33], v[34:35]
	v_cvt_pk_bf16_f32 v32, v36, v37
	v_mul_f32_e32 v36, 0xbfb8aa3b, v28
	v_cvt_pk_bf16_f32 v33, v38, v39
	v_exp_f32_e32 v38, v36
	v_mul_f32_e32 v36, 0xbfb8aa3b, v29
	v_exp_f32_e32 v39, v36
	v_mad_i64_i32 v[36:37], s[14:15], v50, s46, v[112:113]
	v_cvt_pk_bf16_f32 v34, v40, v41
	v_cvt_pk_bf16_f32 v35, v42, v43
	v_add_f32_e32 v38, 1.0, v38
	v_add_f32_e32 v39, 1.0, v39
	v_lshl_add_u64 v[36:37], v[36:37], 0, v[114:115]
	v_rcp_f32_e32 v38, v38
	v_rcp_f32_e32 v39, v39
	global_store_dwordx4 v[36:37], v[32:35], off nt
	v_pk_mul_f32 v[28:29], v[28:29], v[38:39]
	s_nop 0
	v_mul_f32_e32 v32, 0xbfb8aa3b, v30
	v_mul_f32_e32 v33, 0xbfb8aa3b, v31
	v_exp_f32_e32 v32, v32
	v_exp_f32_e32 v33, v33
	v_pk_mul_f32 v[20:21], v[28:29], v[20:21]
	v_add_u32_e32 v34, 0xa0, v144
	v_add_f32_e32 v28, 1.0, v32
	v_add_f32_e32 v29, 1.0, v33
	v_mul_f32_e32 v32, 0xbfb8aa3b, v24
	v_mul_f32_e32 v33, 0xbfb8aa3b, v25
	v_rcp_f32_e32 v28, v28
	v_rcp_f32_e32 v29, v29
	v_exp_f32_e32 v32, v32
	v_exp_f32_e32 v33, v33
	v_pk_mul_f32 v[28:29], v[30:31], v[28:29]
	v_add_f32_e32 v30, 1.0, v32
	v_add_f32_e32 v31, 1.0, v33
	v_mul_f32_e32 v32, 0xbfb8aa3b, v26
	v_mul_f32_e32 v33, 0xbfb8aa3b, v27
	v_exp_f32_e32 v32, v32
	v_exp_f32_e32 v33, v33
	v_rcp_f32_e32 v30, v30
	v_rcp_f32_e32 v31, v31
	v_add_f32_e32 v32, 1.0, v32
	v_add_f32_e32 v33, 1.0, v33
	v_rcp_f32_e32 v32, v32
	v_rcp_f32_e32 v33, v33
	v_pk_mul_f32 v[24:25], v[24:25], v[30:31]
	v_pk_mul_f32 v[22:23], v[28:29], v[22:23]
	v_pk_mul_f32 v[24:25], v[24:25], v[16:17]
	v_pk_mul_f32 v[16:17], v[26:27], v[32:33]
	s_nop 0
	v_pk_mul_f32 v[26:27], v[16:17], v[18:19]
	v_cvt_pk_bf16_f32 v16, v20, v21
	v_mul_f32_e32 v20, 0xbfb8aa3b, v12
	v_cvt_pk_bf16_f32 v17, v22, v23
	v_exp_f32_e32 v22, v20
	v_mul_f32_e32 v20, 0xbfb8aa3b, v13
	v_exp_f32_e32 v23, v20
	v_mad_i64_i32 v[20:21], s[14:15], v34, s46, v[112:113]
	v_cvt_pk_bf16_f32 v18, v24, v25
	v_cvt_pk_bf16_f32 v19, v26, v27
	v_add_f32_e32 v22, 1.0, v22
	v_add_f32_e32 v23, 1.0, v23
	v_lshl_add_u64 v[20:21], v[20:21], 0, v[114:115]
	v_rcp_f32_e32 v22, v22
	v_rcp_f32_e32 v23, v23
	global_store_dwordx4 v[20:21], v[16:19], off nt
	v_pk_mul_f32 v[12:13], v[12:13], v[22:23]
	s_nop 0
	v_mul_f32_e32 v16, 0xbfb8aa3b, v14
	v_mul_f32_e32 v17, 0xbfb8aa3b, v15
	v_exp_f32_e32 v16, v16
	v_exp_f32_e32 v17, v17
	v_pk_mul_f32 v[4:5], v[12:13], v[4:5]
	v_add_u32_e32 v18, 0xb0, v144
	v_add_f32_e32 v12, 1.0, v16
	v_add_f32_e32 v13, 1.0, v17
	v_mul_f32_e32 v16, 0xbfb8aa3b, v8
	v_mul_f32_e32 v17, 0xbfb8aa3b, v9
	v_rcp_f32_e32 v12, v12
	v_rcp_f32_e32 v13, v13
	v_exp_f32_e32 v16, v16
	v_exp_f32_e32 v17, v17
	v_pk_mul_f32 v[12:13], v[14:15], v[12:13]
	v_add_f32_e32 v14, 1.0, v16
	v_add_f32_e32 v15, 1.0, v17
	v_mul_f32_e32 v16, 0xbfb8aa3b, v10
	v_mul_f32_e32 v17, 0xbfb8aa3b, v11
	v_exp_f32_e32 v16, v16
	v_exp_f32_e32 v17, v17
	v_rcp_f32_e32 v14, v14
	v_rcp_f32_e32 v15, v15
	v_add_f32_e32 v16, 1.0, v16
	v_add_f32_e32 v17, 1.0, v17
	v_rcp_f32_e32 v16, v16
	v_rcp_f32_e32 v17, v17
	v_pk_mul_f32 v[8:9], v[8:9], v[14:15]
	v_pk_mul_f32 v[6:7], v[12:13], v[6:7]
	v_pk_mul_f32 v[8:9], v[8:9], v[0:1]
	v_pk_mul_f32 v[0:1], v[10:11], v[16:17]
	s_nop 0
	v_pk_mul_f32 v[10:11], v[0:1], v[2:3]
	v_cvt_pk_bf16_f32 v0, v4, v5
	v_mad_i64_i32 v[4:5], s[14:15], v18, s46, v[112:113]
	v_cvt_pk_bf16_f32 v1, v6, v7
	v_cvt_pk_bf16_f32 v2, v8, v9
	v_cvt_pk_bf16_f32 v3, v10, v11
	v_lshl_add_u64 v[4:5], v[4:5], 0, v[114:115]
	global_store_dwordx4 v[4:5], v[0:3], off nt
	s_cbranch_vccnz .LBB0_3675
	s_andn2_b64 vcc, exec, s[0:1]
	s_cbranch_vccnz .LBB0_3674
	s_barrier
	s_branch .LBB0_3674
